# phase 0: nt cache policy on the once-read f32 weight loads of the transposes (on top of micro_v1)
# speedup vs baseline: 1.0021x; 1.0021x over previous
; #define LAS __attribute__((address_space(3)))
; __device__ __forceinline__ void transpose_item(const float* W, int K, int N, bf16* WT, LAS float* scr, int item, int lane) {
;     const int nkb = K / 64, nb = item / nkb, kb = item % nkb, k0 = 64 * kb, n0 = 64 * nb;
;     f32x4 v[16];
;     { const float* src = W + (size_t)(k0 + (lane >> 4)) * N + n0 + 4 * (lane & 15);
; #pragma unroll
;       for (int i = 0; i < 16; ++i) v[i] = *(const f32x4*)(src + (size_t)(4 * i) * N); }
; #pragma unroll
;     for (int i = 0; i < 16; ++i) { LAS float* d = scr + (4 * i + (lane >> 4)) * 65 + 4 * (lane & 15); d[0] = v[i].x; d[1] = v[i].y; d[2] = v[i].z; d[3] = v[i].w; }
;     asm volatile("s_waitcnt lgkmcnt(0)" ::: "memory");
;     const int c = lane & 7;
; #pragma unroll
;     for (int j = 0; j < 8; ++j) { const int n = (lane >> 3) + 8 * j; const LAS float* s = scr + (8 * c) * 65 + n;
;         u32x4 o; o.x = cvt_pk_bf16(s[0 * 65], s[1 * 65]); o.y = cvt_pk_bf16(s[2 * 65], s[3 * 65]); o.z = cvt_pk_bf16(s[4 * 65], s[5 * 65]); o.w = cvt_pk_bf16(s[6 * 65], s[7 * 65]);
;         *(u32x4*)(WT + (size_t)(n0 + n) * K + k0 + 8 * c) = o; }
;     asm volatile("s_waitcnt lgkmcnt(0)" ::: "memory");
; }
; __device__ __forceinline__ void phase0(const Ptrs& P, ldsp lds, int tid, int lane, int wave, int G) {
;     ...
;     for (int it = gw; it < NLAYER * I_L; it += NGW) {
;         const int l = it / I_L; int r = it % I_L;
;         if (r < I_IN) { transpose_item(P.w_in + (size_t)l * WIN_L, DMODEL, NW, (bf16*)(P.ws + WS_WIN) + (size_t)l * WIN_L, scr, r, lane); continue; } r -= I_IN;
;         if (r < I_P) { transpose_item(P.w_pa + (size_t)l * 1024 * 2048, 1024, 2048, (bf16*)(P.ws + WS_WP) + (size_t)l * WP_L, scr, r, lane); continue; } r -= I_P;
;         if (r < I_P) { transpose_item(P.w_pb + (size_t)l * 1024 * 2048, 1024, 2048, (bf16*)(P.ws + WS_WP) + (size_t)l * WP_L + 2048 * 1024, scr, r, lane); continue; } r -= I_P;
;         if (r < I_P) { transpose_item(P.w_pc + (size_t)l * 1024 * 2048, 1024, 2048, (bf16*)(P.ws + WS_WP) + (size_t)l * WP_L + 2 * 2048 * 1024, scr, r, lane); continue; } r -= I_P;
;         transpose_item(P.w_out + (size_t)l * WOUT_L, 2048, 2048, (bf16*)(P.ws + WS_WOUT) + (size_t)l * WOUT_L, scr, r, lane);
.LBB0_41:
	s_mul_hi_i32 s0, s24, 0x92492493
	s_add_i32 s0, s0, s24
	s_lshr_b32 s1, s0, 31
	s_ashr_i32 s0, s0, 13
	s_add_i32 s12, s0, s1
	s_mul_i32 s0, s12, 0xffffc800
	s_add_i32 s71, s24, s0
	s_ashr_i32 s13, s12, 31
	s_cmpk_gt_i32 s71, 0x2dff
	s_mov_b64 s[0:1], -1
	s_cbranch_scc0 .LBB0_55
	s_cmpk_gt_u32 s71, 0x2fff
	s_cbranch_scc0 .LBB0_52
	s_cmpk_gt_u32 s71, 0x31ff
	s_cbranch_scc0 .LBB0_49
	s_cmpk_gt_u32 s71, 0x33ff
	s_cbranch_scc0 .LBB0_46
	s_lshl_b64 s[0:1], s[12:13], 24
	s_add_u32 s72, s22, s0
	s_addc_u32 s73, s23, s1
	s_lshl_b64 s[0:1], s[12:13], 23
	s_add_u32 s74, s25, s0
	s_addc_u32 s1, s26, s1
	s_and_b32 s75, s34, 0x7c0
	s_mul_i32 s0, s12, 0xffff9000
	s_add_i32 s0, s36, s0
	v_or_b32_e32 v3, s75, v4
	s_and_b32 s0, s0, 0x1ffc0
	v_lshlrev_b32_e32 v48, 13, v3
	v_mov_b32_e32 v49, v1
	v_lshl_add_u64 v[48:49], s[72:73], 0, v[48:49]
	s_lshl_b32 s4, s0, 2
	v_lshl_add_u64 v[48:49], v[48:49], 0, s[4:5]
	v_lshl_add_u64 v[108:109], v[48:49], 0, v[0:1]
	v_add_co_u32_e32 v52, vcc, s38, v108
	s_lshl_b32 s4, s75, 1
	s_nop 0
	v_addc_co_u32_e32 v53, vcc, 0, v109, vcc
	v_add_co_u32_e32 v56, vcc, s39, v108
	global_load_dwordx4 v[48:51], v[108:109], off nt
	s_nop 0
	global_load_dwordx4 v[52:55], v[52:53], off nt
	v_addc_co_u32_e32 v57, vcc, 0, v109, vcc
	v_add_co_u32_e32 v60, vcc, s40, v108
	s_add_u32 s72, s74, s4
	s_nop 0
	v_addc_co_u32_e32 v61, vcc, 0, v109, vcc
	v_add_co_u32_e32 v64, vcc, s41, v108
	global_load_dwordx4 v[56:59], v[56:57], off nt
	s_nop 0
	global_load_dwordx4 v[60:63], v[60:61], off nt
	v_addc_co_u32_e32 v65, vcc, 0, v109, vcc
	v_add_co_u32_e32 v68, vcc, s42, v108
	s_addc_u32 s73, s1, 0
	s_nop 0
	v_addc_co_u32_e32 v69, vcc, 0, v109, vcc
	v_add_co_u32_e32 v72, vcc, s43, v108
	global_load_dwordx4 v[64:67], v[64:65], off nt
	s_nop 0
	global_load_dwordx4 v[68:71], v[68:69], off nt
	v_addc_co_u32_e32 v73, vcc, 0, v109, vcc
	v_add_co_u32_e32 v76, vcc, s47, v108
	v_mov_b32_e32 v3, v1
	s_nop 0
	v_addc_co_u32_e32 v77, vcc, 0, v109, vcc
	v_add_co_u32_e32 v80, vcc, s48, v108
	global_load_dwordx4 v[72:75], v[72:73], off nt
	s_nop 0
	global_load_dwordx4 v[76:79], v[76:77], off nt
	v_addc_co_u32_e32 v81, vcc, 0, v109, vcc
	v_add_co_u32_e32 v84, vcc, s49, v108
	s_nop 1
	v_addc_co_u32_e32 v85, vcc, 0, v109, vcc
	v_add_co_u32_e32 v88, vcc, s50, v108
	global_load_dwordx4 v[80:83], v[80:81], off nt
	s_nop 0
	global_load_dwordx4 v[84:87], v[84:85], off nt
	v_addc_co_u32_e32 v89, vcc, 0, v109, vcc
	v_add_co_u32_e32 v92, vcc, s51, v108
	s_nop 1
	v_addc_co_u32_e32 v93, vcc, 0, v109, vcc
	v_add_co_u32_e32 v96, vcc, s52, v108
	global_load_dwordx4 v[88:91], v[88:89], off nt
	s_nop 0
	global_load_dwordx4 v[92:95], v[92:93], off nt
	v_addc_co_u32_e32 v97, vcc, 0, v109, vcc
	v_add_co_u32_e32 v100, vcc, s53, v108
	s_nop 1
	v_addc_co_u32_e32 v101, vcc, 0, v109, vcc
	global_load_dwordx4 v[96:99], v[96:97], off nt
	s_nop 0
	global_load_dwordx4 v[100:103], v[100:101], off nt
	v_add_co_u32_e32 v104, vcc, s54, v108
	s_nop 1
	v_addc_co_u32_e32 v105, vcc, 0, v109, vcc
	global_load_dwordx4 v[104:107], v[104:105], off nt
	v_add_co_u32_e32 v108, vcc, s55, v108
	s_nop 1
	v_addc_co_u32_e32 v109, vcc, 0, v109, vcc
	global_load_dwordx4 v[108:111], v[108:109], off nt
	s_waitcnt vmcnt(15)
	ds_write2_b32 v5, v48, v49 offset1:1
	ds_write2_b32 v5, v50, v51 offset0:2 offset1:3
	s_waitcnt vmcnt(14)
	ds_write2_b32 v17, v52, v53 offset1:1
	ds_write2_b32 v18, v54, v55 offset1:1
	s_waitcnt vmcnt(13)
	ds_write2_b32 v19, v56, v57 offset1:1
	ds_write2_b32 v20, v58, v59 offset1:1
	s_waitcnt vmcnt(12)
	ds_write2_b32 v21, v60, v61 offset1:1
	ds_write2_b32 v22, v62, v63 offset1:1
	s_waitcnt vmcnt(11)
	ds_write2_b32 v23, v64, v65 offset1:1
	ds_write2_b32 v24, v66, v67 offset1:1
	s_waitcnt vmcnt(10)
	ds_write2_b32 v25, v68, v69 offset1:1
	ds_write2_b32 v26, v70, v71 offset1:1
	s_waitcnt vmcnt(9)
	ds_write2_b32 v27, v72, v73 offset1:1
	ds_write2_b32 v28, v74, v75 offset1:1
	s_waitcnt vmcnt(8)
	ds_write2_b32 v29, v76, v77 offset1:1
	ds_write2_b32 v30, v78, v79 offset1:1
	s_waitcnt vmcnt(7)
	ds_write2_b32 v31, v80, v81 offset1:1
	ds_write2_b32 v32, v82, v83 offset1:1
	s_waitcnt vmcnt(6)
	ds_write2_b32 v33, v84, v85 offset1:1
	ds_write2_b32 v34, v86, v87 offset1:1
	s_waitcnt vmcnt(5)
	ds_write2_b32 v35, v88, v89 offset1:1
	ds_write2_b32 v36, v90, v91 offset1:1
	s_waitcnt vmcnt(4)
	ds_write2_b32 v37, v92, v93 offset1:1
	ds_write2_b32 v38, v94, v95 offset1:1
	s_waitcnt vmcnt(3)
	ds_write2_b32 v39, v96, v97 offset1:1
	ds_write2_b32 v40, v98, v99 offset1:1
	s_waitcnt vmcnt(2)
	ds_write2_b32 v41, v100, v101 offset1:1
	ds_write2_b32 v42, v102, v103 offset1:1
	s_waitcnt vmcnt(1)
	ds_write2_b32 v43, v104, v105 offset1:1
	ds_write2_b32 v44, v106, v107 offset1:1
	s_waitcnt vmcnt(0)
	ds_write2_b32 v45, v108, v109 offset1:1
	ds_write2_b32 v46, v110, v111 offset1:1
	s_waitcnt lgkmcnt(0)
	ds_read2_b32 v[52:53], v7 offset0:65 offset1:73
	ds_read2_b32 v[54:55], v7 offset1:8
	ds_read2_b32 v[56:57], v7 offset0:130 offset1:138
	ds_read2_b32 v[58:59], v7 offset0:195 offset1:203
	ds_read2_b32 v[60:61], v47 offset0:4 offset1:12
	ds_read2_b32 v[62:63], v47 offset0:69 offset1:77
	ds_read2_b32 v[64:65], v47 offset0:134 offset1:142
	ds_read2_b32 v[66:67], v47 offset0:199 offset1:207
	s_waitcnt lgkmcnt(6)
	v_cvt_pk_bf16_f32 v48, v54, v52
	v_or_b32_e32 v52, s0, v6
	v_lshlrev_b32_e32 v68, 12, v52
	v_mov_b32_e32 v69, v1
	v_lshl_add_u64 v[70:71], s[72:73], 0, v[2:3]
	s_waitcnt lgkmcnt(4)
	v_cvt_pk_bf16_f32 v49, v56, v58
	s_waitcnt lgkmcnt(2)
	v_cvt_pk_bf16_f32 v50, v60, v62
	s_waitcnt lgkmcnt(0)
; __device__ __forceinline__ unsigned cvt_pk_bf16(float lo, float hi) { typedef float f2 __attribute__((ext_vector_type(2))); typedef __bf16 b2 __attribute__((ext_vector_type(2))); f2 v = {lo, hi}; b2 b = __builtin_convertvector(v, b2); return __builtin_bit_cast(unsigned, b); }
; #define LAS __attribute__((address_space(3)))
; __device__ __forceinline__ void transpose_item(const float* W, int K, int N, bf16* WT, LAS float* scr, int item, int lane) {
;     const int nkb = K / 64, nb = item / nkb, kb = item % nkb, k0 = 64 * kb, n0 = 64 * nb;
;     f32x4 v[16];
;     { const float* src = W + (size_t)(k0 + (lane >> 4)) * N + n0 + 4 * (lane & 15);
; #pragma unroll
;       for (int i = 0; i < 16; ++i) v[i] = *(const f32x4*)(src + (size_t)(4 * i) * N); }
; #pragma unroll
;     for (int i = 0; i < 16; ++i) { LAS float* d = scr + (4 * i + (lane >> 4)) * 65 + 4 * (lane & 15); d[0] = v[i].x; d[1] = v[i].y; d[2] = v[i].z; d[3] = v[i].w; }
;     asm volatile("s_waitcnt lgkmcnt(0)" ::: "memory");
;     const int c = lane & 7;
; #pragma unroll
;     for (int j = 0; j < 8; ++j) { const int n = (lane >> 3) + 8 * j; const LAS float* s = scr + (8 * c) * 65 + n;
;         u32x4 o; o.x = cvt_pk_bf16(s[0 * 65], s[1 * 65]); o.y = cvt_pk_bf16(s[2 * 65], s[3 * 65]); o.z = cvt_pk_bf16(s[4 * 65], s[5 * 65]); o.w = cvt_pk_bf16(s[6 * 65], s[7 * 65]);
;         *(u32x4*)(WT + (size_t)(n0 + n) * K + k0 + 8 * c) = o; }
	v_cvt_pk_bf16_f32 v51, v64, v66
	v_lshl_add_u64 v[68:69], v[70:71], 0, v[68:69]
	global_store_dwordx4 v[68:69], v[48:51], off
	v_or_b32_e32 v3, s0, v8
	v_lshlrev_b32_e32 v52, 12, v3
	v_cvt_pk_bf16_f32 v48, v55, v53
	v_cvt_pk_bf16_f32 v49, v57, v59
	v_cvt_pk_bf16_f32 v50, v61, v63
	v_cvt_pk_bf16_f32 v51, v65, v67
	ds_read2_b32 v[54:55], v7 offset0:81 offset1:89
	ds_read2_b32 v[56:57], v7 offset0:16 offset1:24
	ds_read2_b32 v[58:59], v7 offset0:146 offset1:154
	ds_read2_b32 v[60:61], v7 offset0:211 offset1:219
	ds_read2_b32 v[62:63], v47 offset0:20 offset1:28
	ds_read2_b32 v[64:65], v47 offset0:85 offset1:93
	ds_read2_b32 v[66:67], v47 offset0:150 offset1:158
	ds_read2_b32 v[68:69], v47 offset0:215 offset1:223
	v_mov_b32_e32 v53, v1
	v_lshl_add_u64 v[52:53], v[70:71], 0, v[52:53]
	v_or_b32_e32 v3, s0, v9
	global_store_dwordx4 v[52:53], v[48:51], off
	v_lshlrev_b32_e32 v52, 12, v3
	v_mov_b32_e32 v53, v1
	s_waitcnt lgkmcnt(6)
	v_cvt_pk_bf16_f32 v48, v56, v54
	s_waitcnt lgkmcnt(4)
	v_cvt_pk_bf16_f32 v49, v58, v60
	s_waitcnt lgkmcnt(2)
	v_cvt_pk_bf16_f32 v50, v62, v64
	s_waitcnt lgkmcnt(0)
	v_cvt_pk_bf16_f32 v51, v66, v68
	v_lshl_add_u64 v[52:53], v[70:71], 0, v[52:53]
	global_store_dwordx4 v[52:53], v[48:51], off
	v_or_b32_e32 v3, s0, v12
	v_lshlrev_b32_e32 v52, 12, v3
	v_cvt_pk_bf16_f32 v48, v57, v55
	v_cvt_pk_bf16_f32 v49, v59, v61
	v_cvt_pk_bf16_f32 v50, v63, v65
	v_cvt_pk_bf16_f32 v51, v67, v69
	ds_read2_b32 v[54:55], v7 offset0:32 offset1:40
	ds_read2_b32 v[56:57], v7 offset0:97 offset1:105
	ds_read2_b32 v[58:59], v7 offset0:162 offset1:170
	ds_read2_b32 v[60:61], v7 offset0:227 offset1:235
	ds_read2_b32 v[62:63], v47 offset0:36 offset1:44
	ds_read2_b32 v[64:65], v47 offset0:101 offset1:109
	ds_read2_b32 v[66:67], v47 offset0:166 offset1:174
	ds_read2_b32 v[68:69], v47 offset0:231 offset1:239
	v_mov_b32_e32 v53, v1
	v_lshl_add_u64 v[52:53], v[70:71], 0, v[52:53]
	v_or_b32_e32 v3, s0, v13
	global_store_dwordx4 v[52:53], v[48:51], off
	v_lshlrev_b32_e32 v52, 12, v3
	v_mov_b32_e32 v53, v1
	s_waitcnt lgkmcnt(6)
	v_cvt_pk_bf16_f32 v48, v54, v56
	s_waitcnt lgkmcnt(4)
	v_cvt_pk_bf16_f32 v49, v58, v60
	s_waitcnt lgkmcnt(2)
	v_cvt_pk_bf16_f32 v50, v62, v64
	s_waitcnt lgkmcnt(0)
	v_cvt_pk_bf16_f32 v51, v66, v68
	v_lshl_add_u64 v[52:53], v[70:71], 0, v[52:53]
	global_store_dwordx4 v[52:53], v[48:51], off
	v_or_b32_e32 v3, s0, v14
	v_lshlrev_b32_e32 v52, 12, v3
	v_cvt_pk_bf16_f32 v48, v55, v57
	v_cvt_pk_bf16_f32 v49, v59, v61
	v_cvt_pk_bf16_f32 v50, v63, v65
	v_cvt_pk_bf16_f32 v51, v67, v69
	ds_read2_b32 v[54:55], v7 offset0:48 offset1:56
	ds_read2_b32 v[56:57], v7 offset0:113 offset1:121
	ds_read2_b32 v[58:59], v7 offset0:178 offset1:186
	ds_read2_b32 v[60:61], v7 offset0:243 offset1:251
	ds_read2_b32 v[62:63], v47 offset0:52 offset1:60
	ds_read2_b32 v[64:65], v47 offset0:117 offset1:125
	ds_read2_b32 v[66:67], v47 offset0:182 offset1:190
	ds_read2_b32 v[68:69], v47 offset0:247 offset1:255
	v_mov_b32_e32 v53, v1
	v_lshl_add_u64 v[52:53], v[70:71], 0, v[52:53]
	v_or_b32_e32 v3, s0, v15
	global_store_dwordx4 v[52:53], v[48:51], off
	v_lshlrev_b32_e32 v52, 12, v3
	v_mov_b32_e32 v53, v1
	s_waitcnt lgkmcnt(6)
	v_cvt_pk_bf16_f32 v48, v54, v56
	s_waitcnt lgkmcnt(4)
	v_cvt_pk_bf16_f32 v49, v58, v60
	s_waitcnt lgkmcnt(2)
	v_cvt_pk_bf16_f32 v50, v62, v64
	s_waitcnt lgkmcnt(0)
	v_cvt_pk_bf16_f32 v51, v66, v68
	v_lshl_add_u64 v[52:53], v[70:71], 0, v[52:53]
	v_or_b32_e32 v3, s0, v16
	global_store_dwordx4 v[52:53], v[48:51], off
	v_lshlrev_b32_e32 v52, 12, v3
	v_mov_b32_e32 v53, v1
	v_cvt_pk_bf16_f32 v48, v55, v57
	v_cvt_pk_bf16_f32 v49, v59, v61
	v_cvt_pk_bf16_f32 v50, v63, v65
	v_cvt_pk_bf16_f32 v51, v67, v69
	v_lshl_add_u64 v[52:53], v[70:71], 0, v[52:53]
	global_store_dwordx4 v[52:53], v[48:51], off
	s_waitcnt lgkmcnt(0)
	s_mov_b64 s[0:1], 0
.LBB0_46:
	s_andn2_b64 vcc, exec, s[0:1]
	s_cbranch_vccnz .LBB0_48
	s_lshl_b64 s[0:1], s[12:13], 23
	s_add_u32 s72, s20, s0
	s_addc_u32 s73, s21, s1
	s_mul_i32 s1, s12, 0xc00000
	s_mul_hi_i32 s0, s12, 0xc00000
	s_add_u32 s1, s10, s1
	s_addc_u32 s74, s11, s0
	s_mul_i32 s0, s12, 0xffff2000
	s_and_b32 s75, s34, 0x3c0
	s_add_i32 s0, s31, s0
	s_addk_i32 s0, 0xf000
	v_or_b32_e32 v3, s75, v4
	s_and_b32 s0, s0, 0x3ffc0
	v_lshlrev_b32_e32 v48, 13, v3
	v_mov_b32_e32 v49, v1
	v_lshl_add_u64 v[48:49], s[72:73], 0, v[48:49]
	s_lshl_b32 s4, s0, 2
	v_lshl_add_u64 v[48:49], v[48:49], 0, s[4:5]
	v_lshl_add_u64 v[108:109], v[48:49], 0, v[0:1]
	v_add_co_u32_e32 v52, vcc, s38, v108
	s_lshl_b32 s4, s75, 1
	s_nop 0
	v_addc_co_u32_e32 v53, vcc, 0, v109, vcc
	v_add_co_u32_e32 v56, vcc, s39, v108
	global_load_dwordx4 v[48:51], v[108:109], off nt
	s_nop 0
	global_load_dwordx4 v[52:55], v[52:53], off nt
	v_addc_co_u32_e32 v57, vcc, 0, v109, vcc
	v_add_co_u32_e32 v60, vcc, s40, v108
	s_add_u32 s72, s1, s4
	s_nop 0
	v_addc_co_u32_e32 v61, vcc, 0, v109, vcc
	v_add_co_u32_e32 v64, vcc, s41, v108
	global_load_dwordx4 v[56:59], v[56:57], off nt
	s_nop 0
	global_load_dwordx4 v[60:63], v[60:61], off nt
	v_addc_co_u32_e32 v65, vcc, 0, v109, vcc
	v_add_co_u32_e32 v68, vcc, s42, v108
	s_addc_u32 s73, s74, 0
	s_nop 0
	v_addc_co_u32_e32 v69, vcc, 0, v109, vcc
	v_add_co_u32_e32 v72, vcc, s43, v108
	global_load_dwordx4 v[64:67], v[64:65], off nt
	s_nop 0
	global_load_dwordx4 v[68:71], v[68:69], off nt
	v_addc_co_u32_e32 v73, vcc, 0, v109, vcc
	v_add_co_u32_e32 v76, vcc, s47, v108
	v_mov_b32_e32 v3, v1
	s_nop 0
	v_addc_co_u32_e32 v77, vcc, 0, v109, vcc
	v_add_co_u32_e32 v80, vcc, s48, v108
	global_load_dwordx4 v[72:75], v[72:73], off nt
	s_nop 0
	global_load_dwordx4 v[76:79], v[76:77], off nt
	v_addc_co_u32_e32 v81, vcc, 0, v109, vcc
	v_add_co_u32_e32 v84, vcc, s49, v108
	s_nop 1
	v_addc_co_u32_e32 v85, vcc, 0, v109, vcc
	v_add_co_u32_e32 v88, vcc, s50, v108
	global_load_dwordx4 v[80:83], v[80:81], off nt
	s_nop 0
	global_load_dwordx4 v[84:87], v[84:85], off nt
	v_addc_co_u32_e32 v89, vcc, 0, v109, vcc
	v_add_co_u32_e32 v92, vcc, s51, v108
	s_nop 1
	v_addc_co_u32_e32 v93, vcc, 0, v109, vcc
	v_add_co_u32_e32 v96, vcc, s52, v108
	global_load_dwordx4 v[88:91], v[88:89], off nt
	s_nop 0
	global_load_dwordx4 v[92:95], v[92:93], off nt
	v_addc_co_u32_e32 v97, vcc, 0, v109, vcc
	v_add_co_u32_e32 v100, vcc, s53, v108
	s_nop 1
	v_addc_co_u32_e32 v101, vcc, 0, v109, vcc
	global_load_dwordx4 v[96:99], v[96:97], off nt
	s_nop 0
	global_load_dwordx4 v[100:103], v[100:101], off nt
	v_add_co_u32_e32 v104, vcc, s54, v108
	s_nop 1
	v_addc_co_u32_e32 v105, vcc, 0, v109, vcc
	global_load_dwordx4 v[104:107], v[104:105], off nt
	v_add_co_u32_e32 v108, vcc, s55, v108
	s_nop 1
	v_addc_co_u32_e32 v109, vcc, 0, v109, vcc
	global_load_dwordx4 v[108:111], v[108:109], off nt
	s_waitcnt vmcnt(15)
; __device__ __forceinline__ unsigned cvt_pk_bf16(float lo, float hi) { typedef float f2 __attribute__((ext_vector_type(2))); typedef __bf16 b2 __attribute__((ext_vector_type(2))); f2 v = {lo, hi}; b2 b = __builtin_convertvector(v, b2); return __builtin_bit_cast(unsigned, b); }
; #define LAS __attribute__((address_space(3)))
; __device__ __forceinline__ void transpose_item(const float* W, int K, int N, bf16* WT, LAS float* scr, int item, int lane) {
;     ...
; #pragma unroll
;     for (int i = 0; i < 16; ++i) { LAS float* d = scr + (4 * i + (lane >> 4)) * 65 + 4 * (lane & 15); d[0] = v[i].x; d[1] = v[i].y; d[2] = v[i].z; d[3] = v[i].w; }
;     asm volatile("s_waitcnt lgkmcnt(0)" ::: "memory");
;     const int c = lane & 7;
; #pragma unroll
;     for (int j = 0; j < 8; ++j) { const int n = (lane >> 3) + 8 * j; const LAS float* s = scr + (8 * c) * 65 + n;
;         u32x4 o; o.x = cvt_pk_bf16(s[0 * 65], s[1 * 65]); o.y = cvt_pk_bf16(s[2 * 65], s[3 * 65]); o.z = cvt_pk_bf16(s[4 * 65], s[5 * 65]); o.w = cvt_pk_bf16(s[6 * 65], s[7 * 65]);
;         *(u32x4*)(WT + (size_t)(n0 + n) * K + k0 + 8 * c) = o; }
;     asm volatile("s_waitcnt lgkmcnt(0)" ::: "memory");
	ds_write2_b32 v5, v48, v49 offset1:1
	ds_write2_b32 v5, v50, v51 offset0:2 offset1:3
	s_waitcnt vmcnt(14)
	ds_write2_b32 v17, v52, v53 offset1:1
	ds_write2_b32 v18, v54, v55 offset1:1
	s_waitcnt vmcnt(13)
	ds_write2_b32 v19, v56, v57 offset1:1
	ds_write2_b32 v20, v58, v59 offset1:1
	s_waitcnt vmcnt(12)
	ds_write2_b32 v21, v60, v61 offset1:1
	ds_write2_b32 v22, v62, v63 offset1:1
	s_waitcnt vmcnt(11)
	ds_write2_b32 v23, v64, v65 offset1:1
	ds_write2_b32 v24, v66, v67 offset1:1
	s_waitcnt vmcnt(10)
	ds_write2_b32 v25, v68, v69 offset1:1
	ds_write2_b32 v26, v70, v71 offset1:1
	s_waitcnt vmcnt(9)
	ds_write2_b32 v27, v72, v73 offset1:1
	ds_write2_b32 v28, v74, v75 offset1:1
	s_waitcnt vmcnt(8)
	ds_write2_b32 v29, v76, v77 offset1:1
	ds_write2_b32 v30, v78, v79 offset1:1
	s_waitcnt vmcnt(7)
	ds_write2_b32 v31, v80, v81 offset1:1
	ds_write2_b32 v32, v82, v83 offset1:1
	s_waitcnt vmcnt(6)
	ds_write2_b32 v33, v84, v85 offset1:1
	ds_write2_b32 v34, v86, v87 offset1:1
	s_waitcnt vmcnt(5)
	ds_write2_b32 v35, v88, v89 offset1:1
	ds_write2_b32 v36, v90, v91 offset1:1
	s_waitcnt vmcnt(4)
	ds_write2_b32 v37, v92, v93 offset1:1
	ds_write2_b32 v38, v94, v95 offset1:1
	s_waitcnt vmcnt(3)
	ds_write2_b32 v39, v96, v97 offset1:1
	ds_write2_b32 v40, v98, v99 offset1:1
	s_waitcnt vmcnt(2)
	ds_write2_b32 v41, v100, v101 offset1:1
	ds_write2_b32 v42, v102, v103 offset1:1
	s_waitcnt vmcnt(1)
	ds_write2_b32 v43, v104, v105 offset1:1
	ds_write2_b32 v44, v106, v107 offset1:1
	s_waitcnt vmcnt(0)
	ds_write2_b32 v45, v108, v109 offset1:1
	ds_write2_b32 v46, v110, v111 offset1:1
	s_waitcnt lgkmcnt(0)
	ds_read2_b32 v[52:53], v7 offset0:65 offset1:73
	ds_read2_b32 v[54:55], v7 offset1:8
	ds_read2_b32 v[56:57], v7 offset0:130 offset1:138
	ds_read2_b32 v[58:59], v7 offset0:195 offset1:203
	ds_read2_b32 v[60:61], v47 offset0:4 offset1:12
	ds_read2_b32 v[62:63], v47 offset0:69 offset1:77
	ds_read2_b32 v[64:65], v47 offset0:134 offset1:142
	ds_read2_b32 v[66:67], v47 offset0:199 offset1:207
	v_lshl_add_u64 v[48:49], s[72:73], 0, v[2:3]
	v_or_b32_e32 v3, s0, v6
	v_lshl_add_u64 v[68:69], v[48:49], 0, s[6:7]
	v_lshlrev_b32_e32 v70, 11, v3
	v_mov_b32_e32 v71, v1
	s_waitcnt lgkmcnt(6)
	v_cvt_pk_bf16_f32 v48, v54, v52
	s_waitcnt lgkmcnt(4)
	v_cvt_pk_bf16_f32 v49, v56, v58
	s_waitcnt lgkmcnt(2)
	v_cvt_pk_bf16_f32 v50, v60, v62
	s_waitcnt lgkmcnt(0)
	v_cvt_pk_bf16_f32 v51, v64, v66
	v_lshl_add_u64 v[70:71], v[68:69], 0, v[70:71]
	global_store_dwordx4 v[70:71], v[48:51], off
	v_or_b32_e32 v3, s0, v8
	v_lshlrev_b32_e32 v52, 11, v3
	v_cvt_pk_bf16_f32 v48, v55, v53
	v_cvt_pk_bf16_f32 v49, v57, v59
	v_cvt_pk_bf16_f32 v50, v61, v63
	v_cvt_pk_bf16_f32 v51, v65, v67
	ds_read2_b32 v[54:55], v7 offset0:81 offset1:89
	ds_read2_b32 v[56:57], v7 offset0:16 offset1:24
	ds_read2_b32 v[58:59], v7 offset0:146 offset1:154
	ds_read2_b32 v[60:61], v7 offset0:211 offset1:219
	ds_read2_b32 v[62:63], v47 offset0:20 offset1:28
	ds_read2_b32 v[64:65], v47 offset0:85 offset1:93
	ds_read2_b32 v[66:67], v47 offset0:150 offset1:158
	ds_read2_b32 v[70:71], v47 offset0:215 offset1:223
	v_mov_b32_e32 v53, v1
	v_lshl_add_u64 v[52:53], v[68:69], 0, v[52:53]
	v_or_b32_e32 v3, s0, v9
	global_store_dwordx4 v[52:53], v[48:51], off
	v_lshlrev_b32_e32 v52, 11, v3
	v_mov_b32_e32 v53, v1
	s_waitcnt lgkmcnt(6)
	v_cvt_pk_bf16_f32 v48, v56, v54
	s_waitcnt lgkmcnt(4)
	v_cvt_pk_bf16_f32 v49, v58, v60
	s_waitcnt lgkmcnt(2)
	v_cvt_pk_bf16_f32 v50, v62, v64
	s_waitcnt lgkmcnt(0)
	v_cvt_pk_bf16_f32 v51, v66, v70
	v_lshl_add_u64 v[52:53], v[68:69], 0, v[52:53]
	global_store_dwordx4 v[52:53], v[48:51], off
	v_or_b32_e32 v3, s0, v12
	v_lshlrev_b32_e32 v52, 11, v3
	v_cvt_pk_bf16_f32 v48, v57, v55
	v_cvt_pk_bf16_f32 v49, v59, v61
	v_cvt_pk_bf16_f32 v50, v63, v65
	v_cvt_pk_bf16_f32 v51, v67, v71
	ds_read2_b32 v[54:55], v7 offset0:32 offset1:40
	ds_read2_b32 v[56:57], v7 offset0:97 offset1:105
	ds_read2_b32 v[58:59], v7 offset0:162 offset1:170
	ds_read2_b32 v[60:61], v7 offset0:227 offset1:235
	ds_read2_b32 v[62:63], v47 offset0:36 offset1:44
	ds_read2_b32 v[64:65], v47 offset0:101 offset1:109
	ds_read2_b32 v[66:67], v47 offset0:166 offset1:174
	ds_read2_b32 v[70:71], v47 offset0:231 offset1:239
	v_mov_b32_e32 v53, v1
	v_lshl_add_u64 v[52:53], v[68:69], 0, v[52:53]
	v_or_b32_e32 v3, s0, v13
	global_store_dwordx4 v[52:53], v[48:51], off
	v_lshlrev_b32_e32 v52, 11, v3
	v_mov_b32_e32 v53, v1
	s_waitcnt lgkmcnt(6)
	v_cvt_pk_bf16_f32 v48, v54, v56
	s_waitcnt lgkmcnt(4)
	v_cvt_pk_bf16_f32 v49, v58, v60
	s_waitcnt lgkmcnt(2)
	v_cvt_pk_bf16_f32 v50, v62, v64
	s_waitcnt lgkmcnt(0)
	v_cvt_pk_bf16_f32 v51, v66, v70
	v_lshl_add_u64 v[52:53], v[68:69], 0, v[52:53]
	global_store_dwordx4 v[52:53], v[48:51], off
	v_or_b32_e32 v3, s0, v14
	v_lshlrev_b32_e32 v52, 11, v3
	v_cvt_pk_bf16_f32 v48, v55, v57
	v_cvt_pk_bf16_f32 v49, v59, v61
	v_cvt_pk_bf16_f32 v50, v63, v65
	v_cvt_pk_bf16_f32 v51, v67, v71
	ds_read2_b32 v[54:55], v7 offset0:48 offset1:56
	ds_read2_b32 v[56:57], v7 offset0:113 offset1:121
	ds_read2_b32 v[58:59], v7 offset0:178 offset1:186
	ds_read2_b32 v[60:61], v7 offset0:243 offset1:251
	ds_read2_b32 v[62:63], v47 offset0:52 offset1:60
	ds_read2_b32 v[64:65], v47 offset0:117 offset1:125
	ds_read2_b32 v[66:67], v47 offset0:182 offset1:190
	ds_read2_b32 v[70:71], v47 offset0:247 offset1:255
	v_mov_b32_e32 v53, v1
	v_lshl_add_u64 v[52:53], v[68:69], 0, v[52:53]
	v_or_b32_e32 v3, s0, v15
	global_store_dwordx4 v[52:53], v[48:51], off
	v_lshlrev_b32_e32 v52, 11, v3
	v_mov_b32_e32 v53, v1
	s_waitcnt lgkmcnt(6)
	v_cvt_pk_bf16_f32 v48, v54, v56
	s_waitcnt lgkmcnt(4)
	v_cvt_pk_bf16_f32 v49, v58, v60
	s_waitcnt lgkmcnt(2)
	v_cvt_pk_bf16_f32 v50, v62, v64
	s_waitcnt lgkmcnt(0)
	v_cvt_pk_bf16_f32 v51, v66, v70
	v_lshl_add_u64 v[52:53], v[68:69], 0, v[52:53]
	v_or_b32_e32 v3, s0, v16
	global_store_dwordx4 v[52:53], v[48:51], off
	v_lshlrev_b32_e32 v52, 11, v3
	v_mov_b32_e32 v53, v1
	v_cvt_pk_bf16_f32 v48, v55, v57
	v_cvt_pk_bf16_f32 v49, v59, v61
	v_cvt_pk_bf16_f32 v50, v63, v65
	v_cvt_pk_bf16_f32 v51, v67, v71
	v_lshl_add_u64 v[52:53], v[68:69], 0, v[52:53]
	global_store_dwordx4 v[52:53], v[48:51], off
	s_waitcnt lgkmcnt(0)

; #define LAS __attribute__((address_space(3)))
; __device__ __forceinline__ void transpose_item(const float* W, int K, int N, bf16* WT, LAS float* scr, int item, int lane) {
;     const int nkb = K / 64, nb = item / nkb, kb = item % nkb, k0 = 64 * kb, n0 = 64 * nb;
;     f32x4 v[16];
;     { const float* src = W + (size_t)(k0 + (lane >> 4)) * N + n0 + 4 * (lane & 15);
; #pragma unroll
;       for (int i = 0; i < 16; ++i) v[i] = *(const f32x4*)(src + (size_t)(4 * i) * N); }
; #pragma unroll
;     for (int i = 0; i < 16; ++i) { LAS float* d = scr + (4 * i + (lane >> 4)) * 65 + 4 * (lane & 15); d[0] = v[i].x; d[1] = v[i].y; d[2] = v[i].z; d[3] = v[i].w; }
;     asm volatile("s_waitcnt lgkmcnt(0)" ::: "memory");
.LBB0_49:
	s_andn2_b64 vcc, exec, s[0:1]
	s_cbranch_vccnz .LBB0_51
	s_lshl_b64 s[0:1], s[12:13], 23
	s_add_u32 s72, s18, s0
	s_addc_u32 s73, s19, s1
	s_mul_i32 s1, s12, 0xc00000
	s_mul_hi_i32 s0, s12, 0xc00000
	s_add_u32 s1, s10, s1
	s_addc_u32 s74, s11, s0
	s_mul_i32 s0, s12, 0xffff2000
	s_and_b32 s75, s34, 0x3c0
	s_add_i32 s0, s31, s0
	s_addk_i32 s0, 0xf800
	v_or_b32_e32 v3, s75, v4
	s_and_b32 s0, s0, 0x3ffc0
	v_lshlrev_b32_e32 v48, 13, v3
	v_mov_b32_e32 v49, v1
	v_lshl_add_u64 v[48:49], s[72:73], 0, v[48:49]
	s_lshl_b32 s4, s0, 2
	v_lshl_add_u64 v[48:49], v[48:49], 0, s[4:5]
	v_lshl_add_u64 v[108:109], v[48:49], 0, v[0:1]
	v_add_co_u32_e32 v52, vcc, s38, v108
	s_lshl_b32 s4, s75, 1
	s_nop 0
	v_addc_co_u32_e32 v53, vcc, 0, v109, vcc
	v_add_co_u32_e32 v56, vcc, s39, v108
	global_load_dwordx4 v[48:51], v[108:109], off nt
	s_nop 0
	global_load_dwordx4 v[52:55], v[52:53], off nt
	v_addc_co_u32_e32 v57, vcc, 0, v109, vcc
	v_add_co_u32_e32 v60, vcc, s40, v108
	s_add_u32 s72, s1, s4
	s_nop 0
	v_addc_co_u32_e32 v61, vcc, 0, v109, vcc
	v_add_co_u32_e32 v64, vcc, s41, v108
	global_load_dwordx4 v[56:59], v[56:57], off nt
	s_nop 0
	global_load_dwordx4 v[60:63], v[60:61], off nt
	v_addc_co_u32_e32 v65, vcc, 0, v109, vcc
	v_add_co_u32_e32 v68, vcc, s42, v108
	s_addc_u32 s73, s74, 0
	s_nop 0
	v_addc_co_u32_e32 v69, vcc, 0, v109, vcc
	v_add_co_u32_e32 v72, vcc, s43, v108
	global_load_dwordx4 v[64:67], v[64:65], off nt
	s_nop 0
	global_load_dwordx4 v[68:71], v[68:69], off nt
	v_addc_co_u32_e32 v73, vcc, 0, v109, vcc
	v_add_co_u32_e32 v76, vcc, s47, v108
	v_mov_b32_e32 v3, v1
	s_nop 0
	v_addc_co_u32_e32 v77, vcc, 0, v109, vcc
	v_add_co_u32_e32 v80, vcc, s48, v108
	global_load_dwordx4 v[72:75], v[72:73], off nt
	s_nop 0
	global_load_dwordx4 v[76:79], v[76:77], off nt
	v_addc_co_u32_e32 v81, vcc, 0, v109, vcc
	v_add_co_u32_e32 v84, vcc, s49, v108
	s_nop 1
	v_addc_co_u32_e32 v85, vcc, 0, v109, vcc
	v_add_co_u32_e32 v88, vcc, s50, v108
	global_load_dwordx4 v[80:83], v[80:81], off nt
	s_nop 0
	global_load_dwordx4 v[84:87], v[84:85], off nt
	v_addc_co_u32_e32 v89, vcc, 0, v109, vcc
	v_add_co_u32_e32 v92, vcc, s51, v108
	s_nop 1
	v_addc_co_u32_e32 v93, vcc, 0, v109, vcc
	v_add_co_u32_e32 v96, vcc, s52, v108
	global_load_dwordx4 v[88:91], v[88:89], off nt
	s_nop 0
	global_load_dwordx4 v[92:95], v[92:93], off nt
	v_addc_co_u32_e32 v97, vcc, 0, v109, vcc
	v_add_co_u32_e32 v100, vcc, s53, v108
	s_nop 1
	v_addc_co_u32_e32 v101, vcc, 0, v109, vcc
	global_load_dwordx4 v[96:99], v[96:97], off nt
	s_nop 0
	global_load_dwordx4 v[100:103], v[100:101], off nt
	v_add_co_u32_e32 v104, vcc, s54, v108
	s_nop 1
	v_addc_co_u32_e32 v105, vcc, 0, v109, vcc
	global_load_dwordx4 v[104:107], v[104:105], off nt
	v_add_co_u32_e32 v108, vcc, s55, v108
	s_nop 1
	v_addc_co_u32_e32 v109, vcc, 0, v109, vcc
	global_load_dwordx4 v[108:111], v[108:109], off nt
	s_waitcnt vmcnt(15)
	ds_write2_b32 v5, v48, v49 offset1:1
	ds_write2_b32 v5, v50, v51 offset0:2 offset1:3
	s_waitcnt vmcnt(14)
	ds_write2_b32 v17, v52, v53 offset1:1
	ds_write2_b32 v18, v54, v55 offset1:1
	s_waitcnt vmcnt(13)
	ds_write2_b32 v19, v56, v57 offset1:1
	ds_write2_b32 v20, v58, v59 offset1:1
	s_waitcnt vmcnt(12)
	ds_write2_b32 v21, v60, v61 offset1:1
	ds_write2_b32 v22, v62, v63 offset1:1
	s_waitcnt vmcnt(11)
	ds_write2_b32 v23, v64, v65 offset1:1
	ds_write2_b32 v24, v66, v67 offset1:1
	s_waitcnt vmcnt(10)
	ds_write2_b32 v25, v68, v69 offset1:1
	ds_write2_b32 v26, v70, v71 offset1:1
	s_waitcnt vmcnt(9)
	ds_write2_b32 v27, v72, v73 offset1:1
	ds_write2_b32 v28, v74, v75 offset1:1
	s_waitcnt vmcnt(8)
	ds_write2_b32 v29, v76, v77 offset1:1
	ds_write2_b32 v30, v78, v79 offset1:1
	s_waitcnt vmcnt(7)
	ds_write2_b32 v31, v80, v81 offset1:1
	ds_write2_b32 v32, v82, v83 offset1:1
	s_waitcnt vmcnt(6)
	ds_write2_b32 v33, v84, v85 offset1:1
	ds_write2_b32 v34, v86, v87 offset1:1
	s_waitcnt vmcnt(5)
	ds_write2_b32 v35, v88, v89 offset1:1
	ds_write2_b32 v36, v90, v91 offset1:1
	s_waitcnt vmcnt(4)
	ds_write2_b32 v37, v92, v93 offset1:1
	ds_write2_b32 v38, v94, v95 offset1:1
	s_waitcnt vmcnt(3)
	ds_write2_b32 v39, v96, v97 offset1:1
	ds_write2_b32 v40, v98, v99 offset1:1
	s_waitcnt vmcnt(2)
	ds_write2_b32 v41, v100, v101 offset1:1
	ds_write2_b32 v42, v102, v103 offset1:1
	s_waitcnt vmcnt(1)
	ds_write2_b32 v43, v104, v105 offset1:1
	ds_write2_b32 v44, v106, v107 offset1:1
	s_waitcnt vmcnt(0)
	ds_write2_b32 v45, v108, v109 offset1:1
	ds_write2_b32 v46, v110, v111 offset1:1
	s_waitcnt lgkmcnt(0)
; __device__ __forceinline__ unsigned cvt_pk_bf16(float lo, float hi) { typedef float f2 __attribute__((ext_vector_type(2))); typedef __bf16 b2 __attribute__((ext_vector_type(2))); f2 v = {lo, hi}; b2 b = __builtin_convertvector(v, b2); return __builtin_bit_cast(unsigned, b); }
; #define LAS __attribute__((address_space(3)))
; __device__ __forceinline__ void transpose_item(const float* W, int K, int N, bf16* WT, LAS float* scr, int item, int lane) {
;     ...
;     const int c = lane & 7;
; #pragma unroll
;     for (int j = 0; j < 8; ++j) { const int n = (lane >> 3) + 8 * j; const LAS float* s = scr + (8 * c) * 65 + n;
;         u32x4 o; o.x = cvt_pk_bf16(s[0 * 65], s[1 * 65]); o.y = cvt_pk_bf16(s[2 * 65], s[3 * 65]); o.z = cvt_pk_bf16(s[4 * 65], s[5 * 65]); o.w = cvt_pk_bf16(s[6 * 65], s[7 * 65]);
;         *(u32x4*)(WT + (size_t)(n0 + n) * K + k0 + 8 * c) = o; }
;     asm volatile("s_waitcnt lgkmcnt(0)" ::: "memory");
	ds_read2_b32 v[52:53], v7 offset0:65 offset1:73
	ds_read2_b32 v[54:55], v7 offset1:8
	ds_read2_b32 v[56:57], v7 offset0:130 offset1:138
	ds_read2_b32 v[58:59], v7 offset0:195 offset1:203
	ds_read2_b32 v[60:61], v47 offset0:4 offset1:12
	ds_read2_b32 v[62:63], v47 offset0:69 offset1:77
	ds_read2_b32 v[64:65], v47 offset0:134 offset1:142
	ds_read2_b32 v[66:67], v47 offset0:199 offset1:207
	v_lshl_add_u64 v[48:49], s[72:73], 0, v[2:3]
	v_or_b32_e32 v3, s0, v6
	v_lshl_add_u64 v[68:69], v[48:49], 0, s[8:9]
	v_lshlrev_b32_e32 v70, 11, v3
	v_mov_b32_e32 v71, v1
	s_waitcnt lgkmcnt(6)
	v_cvt_pk_bf16_f32 v48, v54, v52
	s_waitcnt lgkmcnt(4)
	v_cvt_pk_bf16_f32 v49, v56, v58
	s_waitcnt lgkmcnt(2)
	v_cvt_pk_bf16_f32 v50, v60, v62
	s_waitcnt lgkmcnt(0)
	v_cvt_pk_bf16_f32 v51, v64, v66
	v_lshl_add_u64 v[70:71], v[68:69], 0, v[70:71]
	global_store_dwordx4 v[70:71], v[48:51], off
	v_or_b32_e32 v3, s0, v8
	v_lshlrev_b32_e32 v52, 11, v3
	v_cvt_pk_bf16_f32 v48, v55, v53
	v_cvt_pk_bf16_f32 v49, v57, v59
	v_cvt_pk_bf16_f32 v50, v61, v63
	v_cvt_pk_bf16_f32 v51, v65, v67
	ds_read2_b32 v[54:55], v7 offset0:81 offset1:89
	ds_read2_b32 v[56:57], v7 offset0:16 offset1:24
	ds_read2_b32 v[58:59], v7 offset0:146 offset1:154
	ds_read2_b32 v[60:61], v7 offset0:211 offset1:219
	ds_read2_b32 v[62:63], v47 offset0:20 offset1:28
	ds_read2_b32 v[64:65], v47 offset0:85 offset1:93
	ds_read2_b32 v[66:67], v47 offset0:150 offset1:158
	ds_read2_b32 v[70:71], v47 offset0:215 offset1:223
	v_mov_b32_e32 v53, v1
	v_lshl_add_u64 v[52:53], v[68:69], 0, v[52:53]
	v_or_b32_e32 v3, s0, v9
	global_store_dwordx4 v[52:53], v[48:51], off
	v_lshlrev_b32_e32 v52, 11, v3
	v_mov_b32_e32 v53, v1
	s_waitcnt lgkmcnt(6)
	v_cvt_pk_bf16_f32 v48, v56, v54
	s_waitcnt lgkmcnt(4)
	v_cvt_pk_bf16_f32 v49, v58, v60
	s_waitcnt lgkmcnt(2)
	v_cvt_pk_bf16_f32 v50, v62, v64
	s_waitcnt lgkmcnt(0)
	v_cvt_pk_bf16_f32 v51, v66, v70
	v_lshl_add_u64 v[52:53], v[68:69], 0, v[52:53]
	global_store_dwordx4 v[52:53], v[48:51], off
	v_or_b32_e32 v3, s0, v12
	v_lshlrev_b32_e32 v52, 11, v3
	v_cvt_pk_bf16_f32 v48, v57, v55
	v_cvt_pk_bf16_f32 v49, v59, v61
	v_cvt_pk_bf16_f32 v50, v63, v65
	v_cvt_pk_bf16_f32 v51, v67, v71
	ds_read2_b32 v[54:55], v7 offset0:32 offset1:40
	ds_read2_b32 v[56:57], v7 offset0:97 offset1:105
	ds_read2_b32 v[58:59], v7 offset0:162 offset1:170
	ds_read2_b32 v[60:61], v7 offset0:227 offset1:235
	ds_read2_b32 v[62:63], v47 offset0:36 offset1:44
	ds_read2_b32 v[64:65], v47 offset0:101 offset1:109
	ds_read2_b32 v[66:67], v47 offset0:166 offset1:174
	ds_read2_b32 v[70:71], v47 offset0:231 offset1:239
	v_mov_b32_e32 v53, v1
	v_lshl_add_u64 v[52:53], v[68:69], 0, v[52:53]
	v_or_b32_e32 v3, s0, v13
	global_store_dwordx4 v[52:53], v[48:51], off
	v_lshlrev_b32_e32 v52, 11, v3
	v_mov_b32_e32 v53, v1
	s_waitcnt lgkmcnt(6)
	v_cvt_pk_bf16_f32 v48, v54, v56
	s_waitcnt lgkmcnt(4)
	v_cvt_pk_bf16_f32 v49, v58, v60
	s_waitcnt lgkmcnt(2)
	v_cvt_pk_bf16_f32 v50, v62, v64
	s_waitcnt lgkmcnt(0)
	v_cvt_pk_bf16_f32 v51, v66, v70
	v_lshl_add_u64 v[52:53], v[68:69], 0, v[52:53]
	global_store_dwordx4 v[52:53], v[48:51], off
	v_or_b32_e32 v3, s0, v14
	v_lshlrev_b32_e32 v52, 11, v3
	v_cvt_pk_bf16_f32 v48, v55, v57
	v_cvt_pk_bf16_f32 v49, v59, v61
	v_cvt_pk_bf16_f32 v50, v63, v65
	v_cvt_pk_bf16_f32 v51, v67, v71
	ds_read2_b32 v[54:55], v7 offset0:48 offset1:56
	ds_read2_b32 v[56:57], v7 offset0:113 offset1:121
	ds_read2_b32 v[58:59], v7 offset0:178 offset1:186
	ds_read2_b32 v[60:61], v7 offset0:243 offset1:251
	ds_read2_b32 v[62:63], v47 offset0:52 offset1:60
	ds_read2_b32 v[64:65], v47 offset0:117 offset1:125
	ds_read2_b32 v[66:67], v47 offset0:182 offset1:190
	ds_read2_b32 v[70:71], v47 offset0:247 offset1:255
	v_mov_b32_e32 v53, v1
	v_lshl_add_u64 v[52:53], v[68:69], 0, v[52:53]
	v_or_b32_e32 v3, s0, v15
	global_store_dwordx4 v[52:53], v[48:51], off
	v_lshlrev_b32_e32 v52, 11, v3
	v_mov_b32_e32 v53, v1
	s_waitcnt lgkmcnt(6)
	v_cvt_pk_bf16_f32 v48, v54, v56
	s_waitcnt lgkmcnt(4)
	v_cvt_pk_bf16_f32 v49, v58, v60
	s_waitcnt lgkmcnt(2)
	v_cvt_pk_bf16_f32 v50, v62, v64
	s_waitcnt lgkmcnt(0)
	v_cvt_pk_bf16_f32 v51, v66, v70
	v_lshl_add_u64 v[52:53], v[68:69], 0, v[52:53]
	v_or_b32_e32 v3, s0, v16
	global_store_dwordx4 v[52:53], v[48:51], off
	v_lshlrev_b32_e32 v52, 11, v3
	v_mov_b32_e32 v53, v1
	v_cvt_pk_bf16_f32 v48, v55, v57
	v_cvt_pk_bf16_f32 v49, v59, v61
	v_cvt_pk_bf16_f32 v50, v63, v65
	v_cvt_pk_bf16_f32 v51, v67, v71
	v_lshl_add_u64 v[52:53], v[68:69], 0, v[52:53]
	global_store_dwordx4 v[52:53], v[48:51], off
	s_waitcnt lgkmcnt(0)

; #define LAS __attribute__((address_space(3)))
; __device__ __forceinline__ void transpose_item(const float* W, int K, int N, bf16* WT, LAS float* scr, int item, int lane) {
;     const int nkb = K / 64, nb = item / nkb, kb = item % nkb, k0 = 64 * kb, n0 = 64 * nb;
;     f32x4 v[16];
;     { const float* src = W + (size_t)(k0 + (lane >> 4)) * N + n0 + 4 * (lane & 15);
; #pragma unroll
;       for (int i = 0; i < 16; ++i) v[i] = *(const f32x4*)(src + (size_t)(4 * i) * N); }
; #pragma unroll
;     for (int i = 0; i < 16; ++i) { LAS float* d = scr + (4 * i + (lane >> 4)) * 65 + 4 * (lane & 15); d[0] = v[i].x; d[1] = v[i].y; d[2] = v[i].z; d[3] = v[i].w; }
;     asm volatile("s_waitcnt lgkmcnt(0)" ::: "memory");
.LBB0_52:
	s_andn2_b64 vcc, exec, s[0:1]
	s_cbranch_vccnz .LBB0_54
	s_lshl_b64 s[0:1], s[12:13], 23
	s_add_u32 s72, s16, s0
	s_addc_u32 s73, s17, s1
	s_mul_i32 s1, s12, 0xc00000
	s_mul_hi_i32 s0, s12, 0xc00000
	s_add_u32 s1, s27, s1
	s_addc_u32 s13, s28, s0
	s_and_b32 s74, s34, 0x3c0
	s_mul_i32 s0, s12, 0xffff2000
	s_add_i32 s0, s31, s0
	v_or_b32_e32 v3, s74, v4
	s_and_b32 s0, s0, 0x3ffc0
	v_lshlrev_b32_e32 v48, 13, v3
	v_mov_b32_e32 v49, v1
	v_lshl_add_u64 v[48:49], s[72:73], 0, v[48:49]
	s_lshl_b32 s4, s0, 2
	v_lshl_add_u64 v[48:49], v[48:49], 0, s[4:5]
	v_lshl_add_u64 v[108:109], v[48:49], 0, v[0:1]
	v_add_co_u32_e32 v52, vcc, s38, v108
	s_lshl_b32 s4, s74, 1
	s_nop 0
	v_addc_co_u32_e32 v53, vcc, 0, v109, vcc
	v_add_co_u32_e32 v56, vcc, s39, v108
	global_load_dwordx4 v[48:51], v[108:109], off nt
	s_nop 0
	global_load_dwordx4 v[52:55], v[52:53], off nt
	v_addc_co_u32_e32 v57, vcc, 0, v109, vcc
	v_add_co_u32_e32 v60, vcc, s40, v108
	s_add_u32 s72, s1, s4
	s_nop 0
	v_addc_co_u32_e32 v61, vcc, 0, v109, vcc
	v_add_co_u32_e32 v64, vcc, s41, v108
	global_load_dwordx4 v[56:59], v[56:57], off nt
	s_nop 0
	global_load_dwordx4 v[60:63], v[60:61], off nt
	v_addc_co_u32_e32 v65, vcc, 0, v109, vcc
	v_add_co_u32_e32 v68, vcc, s42, v108
	s_addc_u32 s73, s13, 0
	s_nop 0
	v_addc_co_u32_e32 v69, vcc, 0, v109, vcc
	v_add_co_u32_e32 v72, vcc, s43, v108
	global_load_dwordx4 v[64:67], v[64:65], off nt
	s_nop 0
	global_load_dwordx4 v[68:71], v[68:69], off nt
	v_addc_co_u32_e32 v73, vcc, 0, v109, vcc
	v_add_co_u32_e32 v76, vcc, s47, v108
	v_mov_b32_e32 v3, v1
	s_nop 0
	v_addc_co_u32_e32 v77, vcc, 0, v109, vcc
	v_add_co_u32_e32 v80, vcc, s48, v108
	global_load_dwordx4 v[72:75], v[72:73], off nt
	s_nop 0
	global_load_dwordx4 v[76:79], v[76:77], off nt
	v_addc_co_u32_e32 v81, vcc, 0, v109, vcc
	v_add_co_u32_e32 v84, vcc, s49, v108
	s_nop 1
	v_addc_co_u32_e32 v85, vcc, 0, v109, vcc
	v_add_co_u32_e32 v88, vcc, s50, v108
	global_load_dwordx4 v[80:83], v[80:81], off nt
	s_nop 0
	global_load_dwordx4 v[84:87], v[84:85], off nt
	v_addc_co_u32_e32 v89, vcc, 0, v109, vcc
	v_add_co_u32_e32 v92, vcc, s51, v108
	s_nop 1
	v_addc_co_u32_e32 v93, vcc, 0, v109, vcc
	v_add_co_u32_e32 v96, vcc, s52, v108
	global_load_dwordx4 v[88:91], v[88:89], off nt
	s_nop 0
	global_load_dwordx4 v[92:95], v[92:93], off nt
	v_addc_co_u32_e32 v97, vcc, 0, v109, vcc
	v_add_co_u32_e32 v100, vcc, s53, v108
	s_nop 1
	v_addc_co_u32_e32 v101, vcc, 0, v109, vcc
	global_load_dwordx4 v[96:99], v[96:97], off nt
	s_nop 0
	global_load_dwordx4 v[100:103], v[100:101], off nt
	v_add_co_u32_e32 v104, vcc, s54, v108
	s_nop 1
	v_addc_co_u32_e32 v105, vcc, 0, v109, vcc
	global_load_dwordx4 v[104:107], v[104:105], off nt
	v_add_co_u32_e32 v108, vcc, s55, v108
	s_nop 1
	v_addc_co_u32_e32 v109, vcc, 0, v109, vcc
	global_load_dwordx4 v[108:111], v[108:109], off nt
	s_waitcnt vmcnt(15)
	ds_write2_b32 v5, v48, v49 offset1:1
	ds_write2_b32 v5, v50, v51 offset0:2 offset1:3
	s_waitcnt vmcnt(14)
	ds_write2_b32 v17, v52, v53 offset1:1
	ds_write2_b32 v18, v54, v55 offset1:1
	s_waitcnt vmcnt(13)
	ds_write2_b32 v19, v56, v57 offset1:1
	ds_write2_b32 v20, v58, v59 offset1:1
	s_waitcnt vmcnt(12)
	ds_write2_b32 v21, v60, v61 offset1:1
	ds_write2_b32 v22, v62, v63 offset1:1
	s_waitcnt vmcnt(11)
	ds_write2_b32 v23, v64, v65 offset1:1
	ds_write2_b32 v24, v66, v67 offset1:1
	s_waitcnt vmcnt(10)
	ds_write2_b32 v25, v68, v69 offset1:1
	ds_write2_b32 v26, v70, v71 offset1:1
	s_waitcnt vmcnt(9)
	ds_write2_b32 v27, v72, v73 offset1:1
	ds_write2_b32 v28, v74, v75 offset1:1
	s_waitcnt vmcnt(8)
	ds_write2_b32 v29, v76, v77 offset1:1
	ds_write2_b32 v30, v78, v79 offset1:1
	s_waitcnt vmcnt(7)
	ds_write2_b32 v31, v80, v81 offset1:1
	ds_write2_b32 v32, v82, v83 offset1:1
	s_waitcnt vmcnt(6)
	ds_write2_b32 v33, v84, v85 offset1:1
	ds_write2_b32 v34, v86, v87 offset1:1
	s_waitcnt vmcnt(5)
	ds_write2_b32 v35, v88, v89 offset1:1
	ds_write2_b32 v36, v90, v91 offset1:1
	s_waitcnt vmcnt(4)
	ds_write2_b32 v37, v92, v93 offset1:1
	ds_write2_b32 v38, v94, v95 offset1:1
	s_waitcnt vmcnt(3)
	ds_write2_b32 v39, v96, v97 offset1:1
	ds_write2_b32 v40, v98, v99 offset1:1
	s_waitcnt vmcnt(2)
	ds_write2_b32 v41, v100, v101 offset1:1
	ds_write2_b32 v42, v102, v103 offset1:1
	s_waitcnt vmcnt(1)
	ds_write2_b32 v43, v104, v105 offset1:1
	ds_write2_b32 v44, v106, v107 offset1:1
	s_waitcnt vmcnt(0)
	ds_write2_b32 v45, v108, v109 offset1:1
	ds_write2_b32 v46, v110, v111 offset1:1
	s_waitcnt lgkmcnt(0)
; __device__ __forceinline__ unsigned cvt_pk_bf16(float lo, float hi) { typedef float f2 __attribute__((ext_vector_type(2))); typedef __bf16 b2 __attribute__((ext_vector_type(2))); f2 v = {lo, hi}; b2 b = __builtin_convertvector(v, b2); return __builtin_bit_cast(unsigned, b); }
; #define LAS __attribute__((address_space(3)))
; __device__ __forceinline__ void transpose_item(const float* W, int K, int N, bf16* WT, LAS float* scr, int item, int lane) {
;     ...
;     const int c = lane & 7;
; #pragma unroll
;     for (int j = 0; j < 8; ++j) { const int n = (lane >> 3) + 8 * j; const LAS float* s = scr + (8 * c) * 65 + n;
;         u32x4 o; o.x = cvt_pk_bf16(s[0 * 65], s[1 * 65]); o.y = cvt_pk_bf16(s[2 * 65], s[3 * 65]); o.z = cvt_pk_bf16(s[4 * 65], s[5 * 65]); o.w = cvt_pk_bf16(s[6 * 65], s[7 * 65]);
;         *(u32x4*)(WT + (size_t)(n0 + n) * K + k0 + 8 * c) = o; }
;     asm volatile("s_waitcnt lgkmcnt(0)" ::: "memory");
	ds_read2_b32 v[52:53], v7 offset0:65 offset1:73
	ds_read2_b32 v[54:55], v7 offset1:8
	ds_read2_b32 v[56:57], v7 offset0:130 offset1:138
	ds_read2_b32 v[58:59], v7 offset0:195 offset1:203
	ds_read2_b32 v[60:61], v47 offset0:4 offset1:12
	ds_read2_b32 v[62:63], v47 offset0:69 offset1:77
	ds_read2_b32 v[64:65], v47 offset0:134 offset1:142
	ds_read2_b32 v[66:67], v47 offset0:199 offset1:207
	s_waitcnt lgkmcnt(6)
	v_cvt_pk_bf16_f32 v48, v54, v52
	v_or_b32_e32 v52, s0, v6
	v_lshlrev_b32_e32 v68, 11, v52
	v_mov_b32_e32 v69, v1
	v_lshl_add_u64 v[70:71], s[72:73], 0, v[2:3]
	s_waitcnt lgkmcnt(4)
	v_cvt_pk_bf16_f32 v49, v56, v58
	s_waitcnt lgkmcnt(2)
	v_cvt_pk_bf16_f32 v50, v60, v62
	s_waitcnt lgkmcnt(0)
	v_cvt_pk_bf16_f32 v51, v64, v66
	v_lshl_add_u64 v[68:69], v[70:71], 0, v[68:69]
	global_store_dwordx4 v[68:69], v[48:51], off
	v_or_b32_e32 v3, s0, v8
	v_lshlrev_b32_e32 v52, 11, v3
	v_cvt_pk_bf16_f32 v48, v55, v53
	v_cvt_pk_bf16_f32 v49, v57, v59
	v_cvt_pk_bf16_f32 v50, v61, v63
	v_cvt_pk_bf16_f32 v51, v65, v67
	ds_read2_b32 v[54:55], v7 offset0:81 offset1:89
	ds_read2_b32 v[56:57], v7 offset0:16 offset1:24
	ds_read2_b32 v[58:59], v7 offset0:146 offset1:154
	ds_read2_b32 v[60:61], v7 offset0:211 offset1:219
	ds_read2_b32 v[62:63], v47 offset0:20 offset1:28
	ds_read2_b32 v[64:65], v47 offset0:85 offset1:93
	ds_read2_b32 v[66:67], v47 offset0:150 offset1:158
	ds_read2_b32 v[68:69], v47 offset0:215 offset1:223
	v_mov_b32_e32 v53, v1
	v_lshl_add_u64 v[52:53], v[70:71], 0, v[52:53]
	v_or_b32_e32 v3, s0, v9
	global_store_dwordx4 v[52:53], v[48:51], off
	v_lshlrev_b32_e32 v52, 11, v3
	v_mov_b32_e32 v53, v1
	s_waitcnt lgkmcnt(6)
	v_cvt_pk_bf16_f32 v48, v56, v54
	s_waitcnt lgkmcnt(4)
	v_cvt_pk_bf16_f32 v49, v58, v60
	s_waitcnt lgkmcnt(2)
	v_cvt_pk_bf16_f32 v50, v62, v64
	s_waitcnt lgkmcnt(0)
	v_cvt_pk_bf16_f32 v51, v66, v68
	v_lshl_add_u64 v[52:53], v[70:71], 0, v[52:53]
	global_store_dwordx4 v[52:53], v[48:51], off
	v_or_b32_e32 v3, s0, v12
	v_lshlrev_b32_e32 v52, 11, v3
	v_cvt_pk_bf16_f32 v48, v57, v55
	v_cvt_pk_bf16_f32 v49, v59, v61
	v_cvt_pk_bf16_f32 v50, v63, v65
	v_cvt_pk_bf16_f32 v51, v67, v69
	ds_read2_b32 v[54:55], v7 offset0:32 offset1:40
	ds_read2_b32 v[56:57], v7 offset0:97 offset1:105
	ds_read2_b32 v[58:59], v7 offset0:162 offset1:170
	ds_read2_b32 v[60:61], v7 offset0:227 offset1:235
	ds_read2_b32 v[62:63], v47 offset0:36 offset1:44
	ds_read2_b32 v[64:65], v47 offset0:101 offset1:109
	ds_read2_b32 v[66:67], v47 offset0:166 offset1:174
	ds_read2_b32 v[68:69], v47 offset0:231 offset1:239
	v_mov_b32_e32 v53, v1
	v_lshl_add_u64 v[52:53], v[70:71], 0, v[52:53]
	v_or_b32_e32 v3, s0, v13
	global_store_dwordx4 v[52:53], v[48:51], off
	v_lshlrev_b32_e32 v52, 11, v3
	v_mov_b32_e32 v53, v1
	s_waitcnt lgkmcnt(6)
	v_cvt_pk_bf16_f32 v48, v54, v56
	s_waitcnt lgkmcnt(4)
	v_cvt_pk_bf16_f32 v49, v58, v60
	s_waitcnt lgkmcnt(2)
	v_cvt_pk_bf16_f32 v50, v62, v64
	s_waitcnt lgkmcnt(0)
	v_cvt_pk_bf16_f32 v51, v66, v68
	v_lshl_add_u64 v[52:53], v[70:71], 0, v[52:53]
	global_store_dwordx4 v[52:53], v[48:51], off
	v_or_b32_e32 v3, s0, v14
	v_lshlrev_b32_e32 v52, 11, v3
	v_cvt_pk_bf16_f32 v48, v55, v57
	v_cvt_pk_bf16_f32 v49, v59, v61
	v_cvt_pk_bf16_f32 v50, v63, v65
	v_cvt_pk_bf16_f32 v51, v67, v69
	ds_read2_b32 v[54:55], v7 offset0:48 offset1:56
	ds_read2_b32 v[56:57], v7 offset0:113 offset1:121
	ds_read2_b32 v[58:59], v7 offset0:178 offset1:186
	ds_read2_b32 v[60:61], v7 offset0:243 offset1:251
	ds_read2_b32 v[62:63], v47 offset0:52 offset1:60
	ds_read2_b32 v[64:65], v47 offset0:117 offset1:125
	ds_read2_b32 v[66:67], v47 offset0:182 offset1:190
	ds_read2_b32 v[68:69], v47 offset0:247 offset1:255
	v_mov_b32_e32 v53, v1
	v_lshl_add_u64 v[52:53], v[70:71], 0, v[52:53]
	v_or_b32_e32 v3, s0, v15
	global_store_dwordx4 v[52:53], v[48:51], off
	v_lshlrev_b32_e32 v52, 11, v3
	v_mov_b32_e32 v53, v1
	s_waitcnt lgkmcnt(6)
	v_cvt_pk_bf16_f32 v48, v54, v56
	s_waitcnt lgkmcnt(4)
	v_cvt_pk_bf16_f32 v49, v58, v60
	s_waitcnt lgkmcnt(2)
	v_cvt_pk_bf16_f32 v50, v62, v64
	s_waitcnt lgkmcnt(0)
	v_cvt_pk_bf16_f32 v51, v66, v68
	v_lshl_add_u64 v[52:53], v[70:71], 0, v[52:53]
	v_or_b32_e32 v3, s0, v16
	global_store_dwordx4 v[52:53], v[48:51], off
	v_lshlrev_b32_e32 v52, 11, v3
	v_mov_b32_e32 v53, v1
	v_cvt_pk_bf16_f32 v48, v55, v57
	v_cvt_pk_bf16_f32 v49, v59, v61
	v_cvt_pk_bf16_f32 v50, v63, v65
	v_cvt_pk_bf16_f32 v51, v67, v69
	v_lshl_add_u64 v[52:53], v[70:71], 0, v[52:53]
	global_store_dwordx4 v[52:53], v[48:51], off
	s_waitcnt lgkmcnt(0)

; #define LAS __attribute__((address_space(3)))
; __device__ __forceinline__ void transpose_item(const float* W, int K, int N, bf16* WT, LAS float* scr, int item, int lane) {
;     const int nkb = K / 64, nb = item / nkb, kb = item % nkb, k0 = 64 * kb, n0 = 64 * nb;
;     f32x4 v[16];
;     { const float* src = W + (size_t)(k0 + (lane >> 4)) * N + n0 + 4 * (lane & 15);
; #pragma unroll
;       for (int i = 0; i < 16; ++i) v[i] = *(const f32x4*)(src + (size_t)(4 * i) * N); }
; #pragma unroll
;     for (int i = 0; i < 16; ++i) { LAS float* d = scr + (4 * i + (lane >> 4)) * 65 + 4 * (lane & 15); d[0] = v[i].x; d[1] = v[i].y; d[2] = v[i].z; d[3] = v[i].w; }
;     asm volatile("s_waitcnt lgkmcnt(0)" ::: "memory");
; __device__ __forceinline__ void phase0(const Ptrs& P, ldsp lds, int tid, int lane, int wave, int G) {
;     ...
;         if (r < I_IN) { transpose_item(P.w_in + (size_t)l * WIN_L, DMODEL, NW, (bf16*)(P.ws + WS_WIN) + (size_t)l * WIN_L, scr, r, lane); continue; } r -= I_IN;
.LBB0_55:
	s_andn2_b64 vcc, exec, s[0:1]
	s_cbranch_vccnz .LBB0_40
	s_mul_hi_i32 s1, s12, 0x2e00000
	s_mul_i32 s0, s12, 0x2e00000
	s_lshl_b64 s[12:13], s[0:1], 2
	s_add_u32 s74, s14, s12
	s_addc_u32 s75, s15, s13
	s_lshl_b64 s[0:1], s[0:1], 1
	s_add_u32 s4, s29, s0
	s_addc_u32 s72, s30, s1
	s_bfe_u32 s0, s71, 0x5001a
	s_add_i32 s0, s71, s0
	s_sext_i32_i16 s1, s0
	s_and_b32 s0, s0, 0xffe0
	s_sub_i32 s0, s71, s0
	s_sext_i32_i16 s0, s0
	s_lshl_b32 s12, s0, 6
	v_or_b32_e32 v3, s12, v4
	s_lshl_b32 s0, s1, 1
	v_mul_i32_i24_e32 v48, 0x5c00, v3
	s_andn2_b32 s0, s0, 63
	v_ashrrev_i32_e32 v49, 31, v48
	v_lshl_add_u64 v[48:49], v[48:49], 2, s[74:75]
	s_ashr_i32 s1, s0, 31
	v_lshl_add_u64 v[48:49], s[0:1], 2, v[48:49]
	v_lshl_add_u64 v[108:109], v[48:49], 0, v[0:1]
	v_add_co_u32_e32 v52, vcc, s56, v108
	s_ashr_i32 s13, s12, 31
	s_nop 0
	v_addc_co_u32_e32 v53, vcc, 0, v109, vcc
	v_add_co_u32_e32 v56, vcc, s57, v108
	global_load_dwordx4 v[48:51], v[108:109], off nt
	s_nop 0
	global_load_dwordx4 v[52:55], v[52:53], off nt
	v_addc_co_u32_e32 v57, vcc, 0, v109, vcc
	v_add_co_u32_e32 v60, vcc, s58, v108
	s_lshl_b64 s[12:13], s[12:13], 1
	s_nop 0
	v_addc_co_u32_e32 v61, vcc, 0, v109, vcc
	v_add_co_u32_e32 v64, vcc, s59, v108
	global_load_dwordx4 v[56:59], v[56:57], off nt
	s_nop 0
	global_load_dwordx4 v[60:63], v[60:61], off nt
	v_addc_co_u32_e32 v65, vcc, 0, v109, vcc
	v_add_co_u32_e32 v68, vcc, s60, v108
	s_add_u32 s12, s4, s12
	s_nop 0
	v_addc_co_u32_e32 v69, vcc, 0, v109, vcc
	v_add_co_u32_e32 v72, vcc, s61, v108
	global_load_dwordx4 v[64:67], v[64:65], off nt
	s_nop 0
	global_load_dwordx4 v[68:71], v[68:69], off nt
	v_addc_co_u32_e32 v73, vcc, 0, v109, vcc
	v_add_co_u32_e32 v76, vcc, s62, v108
	s_addc_u32 s13, s72, s13
	s_nop 0
	v_addc_co_u32_e32 v77, vcc, 0, v109, vcc
	v_add_co_u32_e32 v80, vcc, s63, v108
	global_load_dwordx4 v[72:75], v[72:73], off nt
	s_nop 0
	global_load_dwordx4 v[76:79], v[76:77], off nt
	v_addc_co_u32_e32 v81, vcc, 0, v109, vcc
	v_add_co_u32_e32 v84, vcc, s64, v108
	v_mov_b32_e32 v3, v1
	s_nop 0
	v_addc_co_u32_e32 v85, vcc, 0, v109, vcc
	v_add_co_u32_e32 v88, vcc, s65, v108
	global_load_dwordx4 v[80:83], v[80:81], off nt
	s_nop 0
	global_load_dwordx4 v[84:87], v[84:85], off nt
	v_addc_co_u32_e32 v89, vcc, 0, v109, vcc
	v_add_co_u32_e32 v92, vcc, s66, v108
	s_nop 1
	v_addc_co_u32_e32 v93, vcc, 0, v109, vcc
	v_add_co_u32_e32 v96, vcc, s67, v108
	global_load_dwordx4 v[88:91], v[88:89], off nt
	s_nop 0
	global_load_dwordx4 v[92:95], v[92:93], off nt
	v_addc_co_u32_e32 v97, vcc, 0, v109, vcc
	v_add_co_u32_e32 v100, vcc, s68, v108
	s_nop 1
	v_addc_co_u32_e32 v101, vcc, 0, v109, vcc
	global_load_dwordx4 v[96:99], v[96:97], off nt
	s_nop 0
	global_load_dwordx4 v[100:103], v[100:101], off nt
	v_add_co_u32_e32 v104, vcc, s69, v108
	s_nop 1
	v_addc_co_u32_e32 v105, vcc, 0, v109, vcc
	global_load_dwordx4 v[104:107], v[104:105], off nt
	v_add_co_u32_e32 v108, vcc, s70, v108
	s_nop 1
	v_addc_co_u32_e32 v109, vcc, 0, v109, vcc
	global_load_dwordx4 v[108:111], v[108:109], off nt
	s_waitcnt vmcnt(15)
	ds_write2_b32 v5, v48, v49 offset1:1
	ds_write2_b32 v5, v50, v51 offset0:2 offset1:3
	s_waitcnt vmcnt(14)
	ds_write2_b32 v17, v52, v53 offset1:1
	ds_write2_b32 v18, v54, v55 offset1:1
	s_waitcnt vmcnt(13)
	ds_write2_b32 v19, v56, v57 offset1:1
	ds_write2_b32 v20, v58, v59 offset1:1
	s_waitcnt vmcnt(12)
	ds_write2_b32 v21, v60, v61 offset1:1
	ds_write2_b32 v22, v62, v63 offset1:1
	s_waitcnt vmcnt(11)
	ds_write2_b32 v23, v64, v65 offset1:1
	ds_write2_b32 v24, v66, v67 offset1:1
	s_waitcnt vmcnt(10)
	ds_write2_b32 v25, v68, v69 offset1:1
	ds_write2_b32 v26, v70, v71 offset1:1
	s_waitcnt vmcnt(9)
	ds_write2_b32 v27, v72, v73 offset1:1
	ds_write2_b32 v28, v74, v75 offset1:1
	s_waitcnt vmcnt(8)
	ds_write2_b32 v29, v76, v77 offset1:1
	ds_write2_b32 v30, v78, v79 offset1:1
	s_waitcnt vmcnt(7)
	ds_write2_b32 v31, v80, v81 offset1:1
	ds_write2_b32 v32, v82, v83 offset1:1
	s_waitcnt vmcnt(6)
	ds_write2_b32 v33, v84, v85 offset1:1
	ds_write2_b32 v34, v86, v87 offset1:1
	s_waitcnt vmcnt(5)
	ds_write2_b32 v35, v88, v89 offset1:1
	ds_write2_b32 v36, v90, v91 offset1:1
	s_waitcnt vmcnt(4)
	ds_write2_b32 v37, v92, v93 offset1:1
	ds_write2_b32 v38, v94, v95 offset1:1
	s_waitcnt vmcnt(3)
	ds_write2_b32 v39, v96, v97 offset1:1
	ds_write2_b32 v40, v98, v99 offset1:1
	s_waitcnt vmcnt(2)
	ds_write2_b32 v41, v100, v101 offset1:1
	ds_write2_b32 v42, v102, v103 offset1:1
	s_waitcnt vmcnt(1)
	ds_write2_b32 v43, v104, v105 offset1:1
	ds_write2_b32 v44, v106, v107 offset1:1
	s_waitcnt vmcnt(0)
	ds_write2_b32 v45, v108, v109 offset1:1
	ds_write2_b32 v46, v110, v111 offset1:1
	s_waitcnt lgkmcnt(0)
; __device__ __forceinline__ unsigned cvt_pk_bf16(float lo, float hi) { typedef float f2 __attribute__((ext_vector_type(2))); typedef __bf16 b2 __attribute__((ext_vector_type(2))); f2 v = {lo, hi}; b2 b = __builtin_convertvector(v, b2); return __builtin_bit_cast(unsigned, b); }
; #define LAS __attribute__((address_space(3)))
; __device__ __forceinline__ void transpose_item(const float* W, int K, int N, bf16* WT, LAS float* scr, int item, int lane) {
;     ...
;     const int c = lane & 7;
; #pragma unroll
;     for (int j = 0; j < 8; ++j) { const int n = (lane >> 3) + 8 * j; const LAS float* s = scr + (8 * c) * 65 + n;
;         u32x4 o; o.x = cvt_pk_bf16(s[0 * 65], s[1 * 65]); o.y = cvt_pk_bf16(s[2 * 65], s[3 * 65]); o.z = cvt_pk_bf16(s[4 * 65], s[5 * 65]); o.w = cvt_pk_bf16(s[6 * 65], s[7 * 65]);
;         *(u32x4*)(WT + (size_t)(n0 + n) * K + k0 + 8 * c) = o; }
;     asm volatile("s_waitcnt lgkmcnt(0)" ::: "memory");
	ds_read2_b32 v[52:53], v7 offset0:65 offset1:73
	ds_read2_b32 v[54:55], v7 offset1:8
	ds_read2_b32 v[56:57], v7 offset0:130 offset1:138
	ds_read2_b32 v[58:59], v7 offset0:195 offset1:203
	ds_read2_b32 v[60:61], v47 offset0:4 offset1:12
	ds_read2_b32 v[62:63], v47 offset0:69 offset1:77
	ds_read2_b32 v[64:65], v47 offset0:134 offset1:142
	ds_read2_b32 v[66:67], v47 offset0:199 offset1:207
	v_or_b32_e32 v68, s0, v6
	v_ashrrev_i32_e32 v69, 31, v68
	v_lshlrev_b64 v[68:69], 12, v[68:69]
	v_lshl_add_u64 v[70:71], s[12:13], 0, v[2:3]
	s_waitcnt lgkmcnt(6)
	v_cvt_pk_bf16_f32 v48, v54, v52
	s_waitcnt lgkmcnt(4)
	v_cvt_pk_bf16_f32 v49, v56, v58
	s_waitcnt lgkmcnt(2)
	v_cvt_pk_bf16_f32 v50, v60, v62
	s_waitcnt lgkmcnt(0)
	v_cvt_pk_bf16_f32 v51, v64, v66
	v_lshl_add_u64 v[68:69], v[70:71], 0, v[68:69]
	v_or_b32_e32 v52, s0, v8
	global_store_dwordx4 v[68:69], v[48:51], off
	s_nop 1
	v_cvt_pk_bf16_f32 v48, v55, v53
	v_ashrrev_i32_e32 v53, 31, v52
	v_cvt_pk_bf16_f32 v49, v57, v59
	v_cvt_pk_bf16_f32 v50, v61, v63
	v_cvt_pk_bf16_f32 v51, v65, v67
	v_lshlrev_b64 v[52:53], 12, v[52:53]
	ds_read2_b32 v[54:55], v7 offset0:81 offset1:89
	ds_read2_b32 v[56:57], v7 offset0:16 offset1:24
	ds_read2_b32 v[58:59], v7 offset0:146 offset1:154
	ds_read2_b32 v[60:61], v7 offset0:211 offset1:219
	ds_read2_b32 v[62:63], v47 offset0:20 offset1:28
	ds_read2_b32 v[64:65], v47 offset0:85 offset1:93
	ds_read2_b32 v[66:67], v47 offset0:150 offset1:158
	ds_read2_b32 v[68:69], v47 offset0:215 offset1:223
	v_lshl_add_u64 v[52:53], v[70:71], 0, v[52:53]
	global_store_dwordx4 v[52:53], v[48:51], off
	v_or_b32_e32 v52, s0, v9
	v_ashrrev_i32_e32 v53, 31, v52
	v_lshlrev_b64 v[52:53], 12, v[52:53]
	s_waitcnt lgkmcnt(6)
	v_cvt_pk_bf16_f32 v48, v56, v54
	s_waitcnt lgkmcnt(4)
	v_cvt_pk_bf16_f32 v49, v58, v60
	s_waitcnt lgkmcnt(2)
	v_cvt_pk_bf16_f32 v50, v62, v64
	s_waitcnt lgkmcnt(0)
	v_cvt_pk_bf16_f32 v51, v66, v68
	v_lshl_add_u64 v[52:53], v[70:71], 0, v[52:53]
	global_store_dwordx4 v[52:53], v[48:51], off
	v_or_b32_e32 v52, s0, v12
	v_ashrrev_i32_e32 v53, 31, v52
	v_cvt_pk_bf16_f32 v48, v57, v55
	v_cvt_pk_bf16_f32 v49, v59, v61
	v_cvt_pk_bf16_f32 v50, v63, v65
	v_cvt_pk_bf16_f32 v51, v67, v69
	v_lshlrev_b64 v[52:53], 12, v[52:53]
	ds_read2_b32 v[54:55], v7 offset0:32 offset1:40
	ds_read2_b32 v[56:57], v7 offset0:97 offset1:105
	ds_read2_b32 v[58:59], v7 offset0:162 offset1:170
	ds_read2_b32 v[60:61], v7 offset0:227 offset1:235
	ds_read2_b32 v[62:63], v47 offset0:36 offset1:44
	ds_read2_b32 v[64:65], v47 offset0:101 offset1:109
	ds_read2_b32 v[66:67], v47 offset0:166 offset1:174
	ds_read2_b32 v[68:69], v47 offset0:231 offset1:239
	v_lshl_add_u64 v[52:53], v[70:71], 0, v[52:53]
	global_store_dwordx4 v[52:53], v[48:51], off
	v_or_b32_e32 v52, s0, v13
	v_ashrrev_i32_e32 v53, 31, v52
	v_lshlrev_b64 v[52:53], 12, v[52:53]
	s_waitcnt lgkmcnt(6)
	v_cvt_pk_bf16_f32 v48, v54, v56
	s_waitcnt lgkmcnt(4)
	v_cvt_pk_bf16_f32 v49, v58, v60
	s_waitcnt lgkmcnt(2)
	v_cvt_pk_bf16_f32 v50, v62, v64
	s_waitcnt lgkmcnt(0)
	v_cvt_pk_bf16_f32 v51, v66, v68
	v_lshl_add_u64 v[52:53], v[70:71], 0, v[52:53]
	global_store_dwordx4 v[52:53], v[48:51], off
	v_or_b32_e32 v52, s0, v14
	v_ashrrev_i32_e32 v53, 31, v52
	v_cvt_pk_bf16_f32 v48, v55, v57
	v_cvt_pk_bf16_f32 v49, v59, v61
	v_cvt_pk_bf16_f32 v50, v63, v65
	v_cvt_pk_bf16_f32 v51, v67, v69
	v_lshlrev_b64 v[52:53], 12, v[52:53]
	ds_read2_b32 v[54:55], v7 offset0:48 offset1:56
	ds_read2_b32 v[56:57], v7 offset0:113 offset1:121
	ds_read2_b32 v[58:59], v7 offset0:178 offset1:186
	ds_read2_b32 v[60:61], v7 offset0:243 offset1:251
	ds_read2_b32 v[62:63], v47 offset0:52 offset1:60
	ds_read2_b32 v[64:65], v47 offset0:117 offset1:125
	ds_read2_b32 v[66:67], v47 offset0:182 offset1:190
	ds_read2_b32 v[68:69], v47 offset0:247 offset1:255
	v_lshl_add_u64 v[52:53], v[70:71], 0, v[52:53]
	global_store_dwordx4 v[52:53], v[48:51], off
	v_or_b32_e32 v52, s0, v15
	v_ashrrev_i32_e32 v53, 31, v52
	v_lshlrev_b64 v[52:53], 12, v[52:53]
	s_waitcnt lgkmcnt(6)
	v_cvt_pk_bf16_f32 v48, v54, v56
	s_waitcnt lgkmcnt(4)
	v_cvt_pk_bf16_f32 v49, v58, v60
	s_waitcnt lgkmcnt(2)
	v_cvt_pk_bf16_f32 v50, v62, v64
	s_waitcnt lgkmcnt(0)
	v_cvt_pk_bf16_f32 v51, v66, v68
	v_lshl_add_u64 v[52:53], v[70:71], 0, v[52:53]
	global_store_dwordx4 v[52:53], v[48:51], off
	v_or_b32_e32 v52, s0, v16
	v_ashrrev_i32_e32 v53, 31, v52
	v_lshlrev_b64 v[52:53], 12, v[52:53]
	v_cvt_pk_bf16_f32 v48, v55, v57
	v_cvt_pk_bf16_f32 v49, v59, v61
	v_cvt_pk_bf16_f32 v50, v63, v65
	v_cvt_pk_bf16_f32 v51, v67, v69
	v_lshl_add_u64 v[52:53], v[70:71], 0, v[52:53]
	global_store_dwordx4 v[52:53], v[48:51], off
	s_waitcnt lgkmcnt(0)
	s_branch .LBB0_40
